# G1 128-row half tile: 5-stage LDS ring (24 KB stages), tile kt+4 issued in k-step kt, hand-written rolled k-loop
# speedup vs baseline: 1.0017x; 1.0017x over previous
.LBB0_411:
	s_ashr_i32 s1, s47, 1
	s_add_i32 s0, s1, 0x500
	s_lshl_b32 s1, s1, 8
	s_lshl_b32 s2, s47, 7
	s_and_b32 s1, s1, 0x3f00
	s_and_b32 s2, s2, 0x80
	v_mov_b32_e32 v102, v200
	s_or_b32 s56, s1, s2
	v_mov_b32_e32 v8, v200
	s_ashr_i32 s0, s0, 6
	s_lshl_b32 s1, s56, 6
	s_add_u32 s2, s14, s1
	v_ashrrev_i32_e32 v2, 2, v8
	v_lshlrev_b32_e32 v4, 1, v2
	v_lshrrev_b32_e32 v5, 2, v2
	s_addc_u32 s3, s15, 0
	s_ashr_i32 s1, s0, 31
	v_and_b32_e32 v4, 24, v4
	v_and_b32_e32 v5, 4, v5
	v_and_b32_e32 v6, 0xffffffe3, v2
	s_lshl_b64 s[4:5], s[0:1], 14
	v_and_b32_e32 v0, 3, v8
	v_lshrrev_b32_e32 v3, 4, v8
	v_or3_b32 v4, v5, v6, v4
	s_add_u32 s4, s30, s4
	v_bitop3_b32 v0, v3, v0, 2 bitop3:0x6c
	v_ashrrev_i32_e32 v3, 31, v2
	v_ashrrev_i32_e32 v5, 31, v4
	s_addc_u32 s5, s31, s5
	v_lshlrev_b64 v[4:5], 6, v[4:5]
	v_lshlrev_b64 v[6:7], 6, v[2:3]
	v_lshl_add_u64 v[4:5], s[4:5], 0, v[4:5]
	v_lshlrev_b32_e32 v0, 4, v0
	v_lshl_add_u64 v[6:7], s[2:3], 0, v[6:7]
	v_lshl_add_u64 v[4:5], v[4:5], 0, v[0:1]
	v_lshl_add_u64 v[6:7], v[6:7], 0, v[0:1]
	v_lshl_add_u32 v0, v8, 4, 16
	v_add_u32_e32 v3, 0x2000, v0
	v_readfirstlane_b32 s1, v0
	s_mov_b32 m0, s1
	v_readfirstlane_b32 s1, v3
	v_add_u32_e32 v3, 0x4000, v0
	s_waitcnt vmcnt(0)
	s_barrier
	global_load_lds_dwordx4 v[6:7], off
	s_mov_b32 m0, s1
	v_readfirstlane_b32 s1, v3
	v_add_u32_e32 v3, 0x6000, v0
	global_load_lds_dwordx4 v[4:5], off
	v_lshl_add_u64 v[10:11], v[4:5], 0, s[92:93]
	s_mov_b32 m0, s1
	v_readfirstlane_b32 s1, v3
	v_add_u32_e32 v3, 0x8000, v0
	global_load_lds_dwordx4 v[10:11], off
	v_lshl_add_u64 v[10:11], v[6:7], 0, s[94:95]
	s_mov_b32 m0, s1
	v_readfirstlane_b32 s1, v3
	v_add_u32_e32 v3, 0xa000, v0
	v_lshl_add_u64 v[12:13], v[4:5], 0, s[96:97]
	global_load_lds_dwordx4 v[10:11], off
	s_mov_b32 m0, s1
	s_mov_b64 s[2:3], 0x5a000
	v_readfirstlane_b32 s1, v3
	v_add_u32_e32 v3, 0xc000, v0
	global_load_lds_dwordx4 v[12:13], off
	v_lshl_add_u64 v[10:11], v[4:5], 0, s[2:3]
	s_mov_b32 m0, s1
	v_readfirstlane_b32 s1, v3
	v_add_u32_e32 v3, 0xe000, v0
	global_load_lds_dwordx4 v[10:11], off
	v_lshl_add_u64 v[10:11], v[6:7], 0, s[52:53]
	s_mov_b64 s[2:3], 0xb0000
	s_mov_b32 m0, s1
	v_readfirstlane_b32 s1, v3
	v_add_u32_e32 v3, 0x10000, v0
	v_lshl_add_u64 v[12:13], v[4:5], 0, s[2:3]
	global_load_lds_dwordx4 v[10:11], off
	s_mov_b32 m0, s1
	s_mov_b64 s[2:3], 0xb2000
	v_readfirstlane_b32 s1, v3
	v_add_u32_e32 v3, 0x12000, v0
	global_load_lds_dwordx4 v[12:13], off
	v_lshl_add_u64 v[10:11], v[4:5], 0, s[2:3]
	s_mov_b32 m0, s1
	v_readfirstlane_b32 s1, v3
	v_add_u32_e32 v3, 0x14000, v0
	v_ashrrev_i32_e32 v103, 6, v8
	global_load_lds_dwordx4 v[10:11], off
	v_lshl_add_u64 v[10:11], v[6:7], 0, s[66:67]
	s_mov_b64 s[2:3], 0x108000
	s_mov_b32 m0, s1
	v_readfirstlane_b32 s1, v3
	v_add_u32_e32 v3, 0x16000, v0
	v_lshl_add_u64 v[12:13], v[4:5], 0, s[2:3]
	global_load_lds_dwordx4 v[10:11], off
	s_mov_b32 m0, s1
	s_mov_b64 s[2:3], 0x10a000
	v_readfirstlane_b32 s1, v3
	global_load_lds_dwordx4 v[12:13], off
	v_lshl_add_u64 v[10:11], v[4:5], 0, s[2:3]
	s_mov_b32 m0, s1
	s_nop 0
	global_load_lds_dwordx4 v[10:11], off
	s_waitcnt vmcnt(9)
	v_cmp_lt_i32_e32 vcc, 3, v103
	s_barrier
	s_and_saveexec_b64 s[4:5], vcc
	s_cbranch_execz .LBB0_413
	s_barrier
.LBB0_413:
	s_or_b64 exec, exec, s[4:5]
	v_and_b32_e32 v3, 15, v8
	s_mov_b32 s1, 0x3ffffc0
	v_and_or_b32 v2, v2, s1, v3
	s_mov_b64 s[2:3], 0x160000
	v_lshlrev_b32_e32 v105, 6, v2
	v_lshlrev_b32_e32 v2, 6, v8
	v_lshl_add_u64 v[100:101], v[4:5], 0, s[2:3]
	v_lshlrev_b32_e32 v4, 2, v8
	v_and_b32_e32 v5, 48, v8
	v_and_b32_e32 v106, 0x33c0, v2
	v_mov_b32_e32 v2, 0
	s_mov_b64 s[2:3], 0x400000
	v_lshl_add_u64 v[98:99], v[6:7], 0, s[2:3]
	v_bitop3_b32 v104, v4, v5, 32 bitop3:0x6c
	s_mov_b32 s1, 4
	s_mov_b32 s57, 0
	s_mov_b32 s62, 0
	v_mov_b32_e32 v3, v2
	v_mov_b32_e32 v4, v2
	v_mov_b32_e32 v5, v2
	v_mov_b32_e32 v6, v2
	v_mov_b32_e32 v7, v2
	v_mov_b32_e32 v8, v2
	v_mov_b32_e32 v9, v2
	v_mov_b32_e32 v10, v2
	v_mov_b32_e32 v11, v2
	v_mov_b32_e32 v12, v2
	v_mov_b32_e32 v13, v2
	v_mov_b32_e32 v14, v2
	v_mov_b32_e32 v15, v2
	v_mov_b32_e32 v16, v2
	v_mov_b32_e32 v17, v2
	v_mov_b32_e32 v18, v2
	v_mov_b32_e32 v19, v2
	v_mov_b32_e32 v20, v2
	v_mov_b32_e32 v21, v2
	v_mov_b32_e32 v22, v2
	v_mov_b32_e32 v23, v2
	v_mov_b32_e32 v24, v2
	v_mov_b32_e32 v25, v2
	v_mov_b32_e32 v26, v2
	v_mov_b32_e32 v27, v2
	v_mov_b32_e32 v28, v2
	v_mov_b32_e32 v29, v2
	v_mov_b32_e32 v30, v2
	v_mov_b32_e32 v31, v2
	v_mov_b32_e32 v32, v2
	v_mov_b32_e32 v33, v2
	v_mov_b32_e32 v34, v2
	v_mov_b32_e32 v35, v2
	v_mov_b32_e32 v36, v2
	v_mov_b32_e32 v37, v2
	v_mov_b32_e32 v38, v2
	v_mov_b32_e32 v39, v2
	v_mov_b32_e32 v40, v2
	v_mov_b32_e32 v41, v2
	v_mov_b32_e32 v42, v2
	v_mov_b32_e32 v43, v2
	v_mov_b32_e32 v44, v2
	v_mov_b32_e32 v45, v2
	v_mov_b32_e32 v46, v2
	v_mov_b32_e32 v47, v2
	v_mov_b32_e32 v48, v2
	v_mov_b32_e32 v49, v2
	v_mov_b32_e32 v50, v2
	v_mov_b32_e32 v51, v2
	v_mov_b32_e32 v52, v2
	v_mov_b32_e32 v53, v2
	v_mov_b32_e32 v54, v2
	v_mov_b32_e32 v55, v2
	v_mov_b32_e32 v56, v2
	v_mov_b32_e32 v57, v2
	v_mov_b32_e32 v58, v2
	v_mov_b32_e32 v59, v2
	v_mov_b32_e32 v60, v2
	v_mov_b32_e32 v61, v2
	v_mov_b32_e32 v62, v2
	v_mov_b32_e32 v63, v2
	v_mov_b32_e32 v64, v2
	v_mov_b32_e32 v65, v2
	s_branch .LBB0_415
.LBB0_415:
	s_mul_i32 s2, s62, 0x6000
	s_add_i32 s3, s2, 16
	v_add3_u32 v66, s3, v105, v104
	v_add3_u32 v86, s3, v106, v104
	ds_read_b128 v[94:97], v66
	ds_read_b128 v[90:93], v66 offset:1024
	ds_read_b128 v[70:73], v66 offset:2048
	ds_read_b128 v[66:69], v66 offset:3072
	ds_read_b128 v[74:77], v86 offset:8192
	ds_read_b128 v[78:81], v86 offset:9216
	ds_read_b128 v[82:85], v86 offset:10240
	ds_read_b128 v[86:89], v86 offset:11264
	s_cmp_gt_u32 s57, 59
	s_cbranch_scc1 .Lh5_tail
	s_mul_i32 s3, s1, 0x6000
	v_add_u32_e32 v107, s3, v0
	v_add_u32_e32 v108, 0x2000, v107
	v_readfirstlane_b32 s3, v107
	s_mov_b32 m0, s3
	v_readfirstlane_b32 s3, v108
	v_add_u32_e32 v107, 0x4000, v107
	global_load_lds_dwordx4 v[98:99], off
	s_mov_b32 m0, s3
	v_readfirstlane_b32 s3, v107
	global_load_lds_dwordx4 v[100:101], off
	v_lshl_add_u64 v[108:109], v[100:101], 0, s[92:93]
	s_mov_b32 m0, s3
	v_lshl_add_u64 v[98:99], v[98:99], 0, s[94:95]
	global_load_lds_dwordx4 v[108:109], off
	s_waitcnt vmcnt(9) lgkmcnt(0)
	v_lshl_add_u64 v[100:101], v[100:101], 0, s[96:97]
	s_branch .Lh5_m
.Lh5_tail:
	s_cmp_lg_u32 s57, 60
	s_cbranch_scc1 .Lh5_t1
	s_waitcnt vmcnt(6) lgkmcnt(0)
	s_branch .Lh5_m
.Lh5_t1:
	s_cmp_lg_u32 s57, 61
	s_cbranch_scc1 .Lh5_t2
	s_waitcnt vmcnt(3) lgkmcnt(0)
	s_branch .Lh5_m
.Lh5_t2:
	s_waitcnt vmcnt(0) lgkmcnt(0)
.Lh5_m:
	s_barrier
	s_waitcnt lgkmcnt(0)
	v_mfma_f32_16x16x32_bf16 v[62:65], v[74:77], v[94:97], v[62:65]
	v_mfma_f32_16x16x32_bf16 v[58:61], v[78:81], v[94:97], v[58:61]
	v_mfma_f32_16x16x32_bf16 v[54:57], v[82:85], v[94:97], v[54:57]
	v_mfma_f32_16x16x32_bf16 v[50:53], v[86:89], v[94:97], v[50:53]
	v_mfma_f32_16x16x32_bf16 v[46:49], v[74:77], v[90:93], v[46:49]
	v_mfma_f32_16x16x32_bf16 v[42:45], v[78:81], v[90:93], v[42:45]
	v_mfma_f32_16x16x32_bf16 v[38:41], v[82:85], v[90:93], v[38:41]
	v_mfma_f32_16x16x32_bf16 v[34:37], v[86:89], v[90:93], v[34:37]
	v_mfma_f32_16x16x32_bf16 v[30:33], v[74:77], v[70:73], v[30:33]
	v_mfma_f32_16x16x32_bf16 v[26:29], v[78:81], v[70:73], v[26:29]
	v_mfma_f32_16x16x32_bf16 v[22:25], v[82:85], v[70:73], v[22:25]
	v_mfma_f32_16x16x32_bf16 v[18:21], v[86:89], v[70:73], v[18:21]
	v_mfma_f32_16x16x32_bf16 v[14:17], v[74:77], v[66:69], v[14:17]
	v_mfma_f32_16x16x32_bf16 v[10:13], v[78:81], v[66:69], v[10:13]
	v_mfma_f32_16x16x32_bf16 v[6:9], v[82:85], v[66:69], v[6:9]
	v_mfma_f32_16x16x32_bf16 v[2:5], v[86:89], v[66:69], v[2:5]
	s_barrier
	s_add_i32 s62, s62, 1
	s_cmp_eq_u32 s62, 5
	s_cselect_b32 s62, 0, s62
	s_add_i32 s1, s1, 1
	s_cmp_eq_u32 s1, 5
	s_cselect_b32 s1, 0, s1
	s_add_i32 s57, s57, 1
	s_cmp_eq_u32 s57, 64
	s_cbranch_scc0 .LBB0_415
